# p0b transpose items: both 16-row load batches in flight before the first is consumed
# baseline (speedup 1.0000x reference)
.LBB0_371:
	s_lshl_b32 s8, s18, 1
	s_lshl_b32 s9, s15, 1
	v_add_u32_e32 v58, s8, v36
	v_add_u32_e32 v56, s9, v31
	v_add_u32_e32 v60, s9, v33
	v_add_u32_e32 v62, s8, v38
	v_add_u32_e32 v64, s9, v37
	v_add_u32_e32 v66, s8, v40
	v_add_u32_e32 v68, s9, v39
	v_add_u32_e32 v70, s8, v42
	v_add_u32_e32 v72, s9, v41
	v_add_u32_e32 v74, s8, v44
	v_add_u32_e32 v76, s9, v43
	v_add_u32_e32 v78, s8, v46
	v_add_u32_e32 v80, s9, v45
	v_add_u32_e32 v82, s8, v48
	v_add_u32_e32 v84, s9, v47
	v_add_u32_e32 v86, s8, v50
	v_ashrrev_i32_e32 v59, 31, v58
	v_ashrrev_i32_e32 v57, 31, v56
	v_ashrrev_i32_e32 v63, 31, v62
	v_ashrrev_i32_e32 v61, 31, v60
	v_ashrrev_i32_e32 v67, 31, v66
	v_ashrrev_i32_e32 v65, 31, v64
	v_ashrrev_i32_e32 v71, 31, v70
	v_ashrrev_i32_e32 v69, 31, v68
	v_ashrrev_i32_e32 v75, 31, v74
	v_ashrrev_i32_e32 v73, 31, v72
	v_ashrrev_i32_e32 v79, 31, v78
	v_ashrrev_i32_e32 v77, 31, v76
	v_ashrrev_i32_e32 v83, 31, v82
	v_ashrrev_i32_e32 v81, 31, v80
	v_ashrrev_i32_e32 v87, 31, v86
	v_ashrrev_i32_e32 v85, 31, v84
	v_lshlrev_b64 v[58:59], 12, v[58:59]
	v_lshlrev_b64 v[56:57], 12, v[56:57]
	v_lshlrev_b64 v[60:61], 12, v[60:61]
	v_lshlrev_b64 v[62:63], 12, v[62:63]
	v_lshlrev_b64 v[64:65], 12, v[64:65]
	v_lshlrev_b64 v[66:67], 12, v[66:67]
	v_lshlrev_b64 v[68:69], 12, v[68:69]
	v_lshlrev_b64 v[70:71], 12, v[70:71]
	v_lshlrev_b64 v[72:73], 12, v[72:73]
	v_lshlrev_b64 v[74:75], 12, v[74:75]
	v_lshlrev_b64 v[76:77], 12, v[76:77]
	v_lshlrev_b64 v[78:79], 12, v[78:79]
	v_lshlrev_b64 v[80:81], 12, v[80:81]
	v_lshlrev_b64 v[82:83], 12, v[82:83]
	v_lshlrev_b64 v[84:85], 12, v[84:85]
	v_lshlrev_b64 v[86:87], 12, v[86:87]
	v_lshl_add_u64 v[58:59], v[34:35], 0, v[58:59]
	v_lshl_add_u64 v[56:57], v[34:35], 0, v[56:57]
	v_lshl_add_u64 v[62:63], v[34:35], 0, v[62:63]
	v_lshl_add_u64 v[60:61], v[34:35], 0, v[60:61]
	v_lshl_add_u64 v[66:67], v[34:35], 0, v[66:67]
	v_lshl_add_u64 v[64:65], v[34:35], 0, v[64:65]
	v_lshl_add_u64 v[70:71], v[34:35], 0, v[70:71]
	v_lshl_add_u64 v[68:69], v[34:35], 0, v[68:69]
	v_lshl_add_u64 v[74:75], v[34:35], 0, v[74:75]
	v_lshl_add_u64 v[72:73], v[34:35], 0, v[72:73]
	v_lshl_add_u64 v[78:79], v[34:35], 0, v[78:79]
	v_lshl_add_u64 v[76:77], v[34:35], 0, v[76:77]
	v_lshl_add_u64 v[82:83], v[34:35], 0, v[82:83]
	v_lshl_add_u64 v[80:81], v[34:35], 0, v[80:81]
	v_lshl_add_u64 v[86:87], v[34:35], 0, v[86:87]
	v_lshl_add_u64 v[84:85], v[34:35], 0, v[84:85]
	global_load_dword v88, v[58:59], off
	global_load_dword v89, v[56:57], off
	global_load_dword v90, v[62:63], off
	global_load_dword v91, v[60:61], off
	global_load_dword v92, v[66:67], off
	global_load_dword v93, v[64:65], off
	global_load_dword v94, v[70:71], off
	global_load_dword v95, v[68:69], off
	global_load_dword v96, v[74:75], off
	global_load_dword v97, v[72:73], off
	global_load_dword v98, v[78:79], off
	global_load_dword v99, v[76:77], off
	global_load_dword v100, v[82:83], off
	global_load_dword v101, v[80:81], off
	global_load_dword v102, v[86:87], off
	global_load_dword v103, v[84:85], off
	s_add_i32 s18, s18, 16
	s_add_i32 s15, s15, 16
	s_add_i32 s19, s19, -16
	v_add_u32_e32 v56, s8, v0
	v_add_u32_e32 v58, s9, v1
	v_add_u32_e32 v62, s9, v5
	v_add_u32_e32 v60, s8, v20
	v_add_u32_e32 v66, s9, v7
	v_add_u32_e32 v64, s8, v22
	v_add_u32_e32 v70, s9, v21
	v_add_u32_e32 v68, s8, v24
	v_add_u32_e32 v74, s9, v23
	v_add_u32_e32 v72, s8, v26
	v_add_u32_e32 v78, s9, v25
	v_add_u32_e32 v76, s8, v28
	v_add_u32_e32 v82, s9, v27
	v_add_u32_e32 v80, s8, v30
	v_add_u32_e32 v86, s9, v29
	v_add_u32_e32 v84, s8, v32
	s_cmp_lg_u32 s19, 0
	v_mad_u64_u32 v[56:57], s[8:9], v56, s16, v[4:5]
	v_mad_u64_u32 v[58:59], s[8:9], v58, s16, v[4:5]
	v_mad_u64_u32 v[60:61], s[8:9], v60, s16, v[4:5]
	v_mad_u64_u32 v[62:63], s[8:9], v62, s16, v[4:5]
	v_mad_u64_u32 v[64:65], s[8:9], v64, s16, v[4:5]
	v_mad_u64_u32 v[66:67], s[8:9], v66, s16, v[4:5]
	v_mad_u64_u32 v[68:69], s[8:9], v68, s16, v[4:5]
	v_mad_u64_u32 v[70:71], s[8:9], v70, s16, v[4:5]
	v_mad_u64_u32 v[72:73], s[8:9], v72, s16, v[4:5]
	v_mad_u64_u32 v[74:75], s[8:9], v74, s16, v[4:5]
	v_mad_u64_u32 v[76:77], s[8:9], v76, s16, v[4:5]
	v_mad_u64_u32 v[78:79], s[8:9], v78, s16, v[4:5]
	v_mad_u64_u32 v[80:81], s[8:9], v80, s16, v[4:5]
	v_mad_u64_u32 v[82:83], s[8:9], v82, s16, v[4:5]
	v_mad_u64_u32 v[84:85], s[8:9], v84, s16, v[4:5]
	v_mad_u64_u32 v[86:87], s[8:9], v86, s16, v[4:5]
	s_lshl_b32 s8, s18, 1
	s_lshl_b32 s9, s15, 1
	v_add_u32_e32 v106, s8, v36
	v_add_u32_e32 v104, s9, v31
	v_add_u32_e32 v108, s9, v33
	v_add_u32_e32 v110, s8, v38
	v_add_u32_e32 v112, s9, v37
	v_add_u32_e32 v114, s8, v40
	v_add_u32_e32 v116, s9, v39
	v_add_u32_e32 v118, s8, v42
	v_add_u32_e32 v120, s9, v41
	v_add_u32_e32 v122, s8, v44
	v_add_u32_e32 v124, s9, v43
	v_add_u32_e32 v126, s8, v46
	v_add_u32_e32 v128, s9, v45
	v_add_u32_e32 v130, s8, v48
	v_add_u32_e32 v132, s9, v47
	v_add_u32_e32 v134, s8, v50
	v_ashrrev_i32_e32 v107, 31, v106
	v_ashrrev_i32_e32 v105, 31, v104
	v_ashrrev_i32_e32 v111, 31, v110
	v_ashrrev_i32_e32 v109, 31, v108
	v_ashrrev_i32_e32 v115, 31, v114
	v_ashrrev_i32_e32 v113, 31, v112
	v_ashrrev_i32_e32 v119, 31, v118
	v_ashrrev_i32_e32 v117, 31, v116
	v_ashrrev_i32_e32 v123, 31, v122
	v_ashrrev_i32_e32 v121, 31, v120
	v_ashrrev_i32_e32 v127, 31, v126
	v_ashrrev_i32_e32 v125, 31, v124
	v_ashrrev_i32_e32 v131, 31, v130
	v_ashrrev_i32_e32 v129, 31, v128
	v_ashrrev_i32_e32 v135, 31, v134
	v_ashrrev_i32_e32 v133, 31, v132
	v_lshlrev_b64 v[106:107], 12, v[106:107]
	v_lshlrev_b64 v[104:105], 12, v[104:105]
	v_lshlrev_b64 v[108:109], 12, v[108:109]
	v_lshlrev_b64 v[110:111], 12, v[110:111]
	v_lshlrev_b64 v[112:113], 12, v[112:113]
	v_lshlrev_b64 v[114:115], 12, v[114:115]
	v_lshlrev_b64 v[116:117], 12, v[116:117]
	v_lshlrev_b64 v[118:119], 12, v[118:119]
	v_lshlrev_b64 v[120:121], 12, v[120:121]
	v_lshlrev_b64 v[122:123], 12, v[122:123]
	v_lshlrev_b64 v[124:125], 12, v[124:125]
	v_lshlrev_b64 v[126:127], 12, v[126:127]
	v_lshlrev_b64 v[128:129], 12, v[128:129]
	v_lshlrev_b64 v[130:131], 12, v[130:131]
	v_lshlrev_b64 v[132:133], 12, v[132:133]
	v_lshlrev_b64 v[134:135], 12, v[134:135]
	v_lshl_add_u64 v[106:107], v[34:35], 0, v[106:107]
	v_lshl_add_u64 v[104:105], v[34:35], 0, v[104:105]
	v_lshl_add_u64 v[110:111], v[34:35], 0, v[110:111]
	v_lshl_add_u64 v[108:109], v[34:35], 0, v[108:109]
	v_lshl_add_u64 v[114:115], v[34:35], 0, v[114:115]
	v_lshl_add_u64 v[112:113], v[34:35], 0, v[112:113]
	v_lshl_add_u64 v[118:119], v[34:35], 0, v[118:119]
	v_lshl_add_u64 v[116:117], v[34:35], 0, v[116:117]
	v_lshl_add_u64 v[122:123], v[34:35], 0, v[122:123]
	v_lshl_add_u64 v[120:121], v[34:35], 0, v[120:121]
	v_lshl_add_u64 v[126:127], v[34:35], 0, v[126:127]
	v_lshl_add_u64 v[124:125], v[34:35], 0, v[124:125]
	v_lshl_add_u64 v[130:131], v[34:35], 0, v[130:131]
	v_lshl_add_u64 v[128:129], v[34:35], 0, v[128:129]
	v_lshl_add_u64 v[134:135], v[34:35], 0, v[134:135]
	v_lshl_add_u64 v[132:133], v[34:35], 0, v[132:133]
	global_load_dword v136, v[106:107], off
	global_load_dword v137, v[104:105], off
	global_load_dword v138, v[110:111], off
	global_load_dword v139, v[108:109], off
	global_load_dword v140, v[114:115], off
	global_load_dword v141, v[112:113], off
	global_load_dword v142, v[118:119], off
	global_load_dword v143, v[116:117], off
	global_load_dword v144, v[122:123], off
	global_load_dword v145, v[120:121], off
	global_load_dword v146, v[126:127], off
	global_load_dword v147, v[124:125], off
	global_load_dword v148, v[130:131], off
	global_load_dword v149, v[128:129], off
	global_load_dword v150, v[134:135], off
	global_load_dword v151, v[132:133], off
	s_add_i32 s18, s18, 16
	s_add_i32 s15, s15, 16
	s_add_i32 s19, s19, -16
	v_add_u32_e32 v104, s8, v0
	v_add_u32_e32 v106, s9, v1
	v_add_u32_e32 v110, s9, v5
	v_add_u32_e32 v108, s8, v20
	v_add_u32_e32 v114, s9, v7
	v_add_u32_e32 v112, s8, v22
	v_add_u32_e32 v118, s9, v21
	v_add_u32_e32 v116, s8, v24
	v_add_u32_e32 v122, s9, v23
	v_add_u32_e32 v120, s8, v26
	v_add_u32_e32 v126, s9, v25
	v_add_u32_e32 v124, s8, v28
	v_add_u32_e32 v130, s9, v27
	v_add_u32_e32 v128, s8, v30
	v_add_u32_e32 v134, s9, v29
	v_add_u32_e32 v132, s8, v32
	s_cmp_lg_u32 s19, 0
	v_mad_u64_u32 v[104:105], s[8:9], v104, s16, v[4:5]
	v_mad_u64_u32 v[106:107], s[8:9], v106, s16, v[4:5]
	v_mad_u64_u32 v[108:109], s[8:9], v108, s16, v[4:5]
	v_mad_u64_u32 v[110:111], s[8:9], v110, s16, v[4:5]
	v_mad_u64_u32 v[112:113], s[8:9], v112, s16, v[4:5]
	v_mad_u64_u32 v[114:115], s[8:9], v114, s16, v[4:5]
	v_mad_u64_u32 v[116:117], s[8:9], v116, s16, v[4:5]
	v_mad_u64_u32 v[118:119], s[8:9], v118, s16, v[4:5]
	v_mad_u64_u32 v[120:121], s[8:9], v120, s16, v[4:5]
	v_mad_u64_u32 v[122:123], s[8:9], v122, s16, v[4:5]
	v_mad_u64_u32 v[124:125], s[8:9], v124, s16, v[4:5]
	v_mad_u64_u32 v[126:127], s[8:9], v126, s16, v[4:5]
	v_mad_u64_u32 v[128:129], s[8:9], v128, s16, v[4:5]
	v_mad_u64_u32 v[130:131], s[8:9], v130, s16, v[4:5]
	v_mad_u64_u32 v[132:133], s[8:9], v132, s16, v[4:5]
	v_mad_u64_u32 v[134:135], s[8:9], v134, s16, v[4:5]
	s_waitcnt vmcnt(31)
	ds_write_b32 v56, v88
	s_waitcnt vmcnt(30)
	ds_write_b32 v58, v89
	s_waitcnt vmcnt(29)
	ds_write_b32 v60, v90
	s_waitcnt vmcnt(28)
	ds_write_b32 v62, v91
	s_waitcnt vmcnt(27)
	ds_write_b32 v64, v92
	s_waitcnt vmcnt(26)
	ds_write_b32 v66, v93
	s_waitcnt vmcnt(25)
	ds_write_b32 v68, v94
	s_waitcnt vmcnt(24)
	ds_write_b32 v70, v95
	s_waitcnt vmcnt(23)
	ds_write_b32 v72, v96
	s_waitcnt vmcnt(22)
	ds_write_b32 v74, v97
	s_waitcnt vmcnt(21)
	ds_write_b32 v76, v98
	s_waitcnt vmcnt(20)
	ds_write_b32 v78, v99
	s_waitcnt vmcnt(19)
	ds_write_b32 v80, v100
	s_waitcnt vmcnt(18)
	ds_write_b32 v82, v101
	s_waitcnt vmcnt(17)
	ds_write_b32 v84, v102
	s_waitcnt vmcnt(16)
	ds_write_b32 v86, v103
	s_waitcnt vmcnt(15)
	ds_write_b32 v104, v136
	s_waitcnt vmcnt(14)
	ds_write_b32 v106, v137
	s_waitcnt vmcnt(13)
	ds_write_b32 v108, v138
	s_waitcnt vmcnt(12)
	ds_write_b32 v110, v139
	s_waitcnt vmcnt(11)
	ds_write_b32 v112, v140
	s_waitcnt vmcnt(10)
	ds_write_b32 v114, v141
	s_waitcnt vmcnt(9)
	ds_write_b32 v116, v142
	s_waitcnt vmcnt(8)
	ds_write_b32 v118, v143
	s_waitcnt vmcnt(7)
	ds_write_b32 v120, v144
	s_waitcnt vmcnt(6)
	ds_write_b32 v122, v145
	s_waitcnt vmcnt(5)
	ds_write_b32 v124, v146
	s_waitcnt vmcnt(4)
	ds_write_b32 v126, v147
	s_waitcnt vmcnt(3)
	ds_write_b32 v128, v148
	s_waitcnt vmcnt(2)
	ds_write_b32 v130, v149
	s_waitcnt vmcnt(1)
	ds_write_b32 v132, v150
	s_waitcnt vmcnt(0)
	ds_write_b32 v134, v151
	s_and_b64 s[8:9], s[36:37], exec
	s_cselect_b32 s8, 0x580000, 0
	v_readlane_b32 s9, v254, 41
	s_waitcnt lgkmcnt(0)
	s_add_u32 s8, s9, s8
	v_readlane_b32 s9, v254, 43
	s_addc_u32 s9, s9, 0
	s_lshl_b32 s0, s0, 1
	ds_read2_b32 v[34:35], v51 offset1:33
	s_add_u32 s8, s8, s0
	s_waitcnt lgkmcnt(0)
	v_cvt_pk_bf16_f32 v34, v34, v35
	ds_read2_b32 v[36:37], v51 offset0:66 offset1:99
	v_lshlrev_b32_e32 v38, 1, v6
	v_mov_b32_e32 v39, v3
	s_addc_u32 s9, s9, 0
	s_waitcnt lgkmcnt(0)
	v_cvt_pk_bf16_f32 v35, v36, v37
	ds_read2_b32 v[36:37], v51 offset0:132 offset1:165
	v_add_u32_e32 v31, s14, v49
	v_lshl_add_u64 v[38:39], s[8:9], 0, v[38:39]
	s_waitcnt lgkmcnt(0)
	v_cvt_pk_bf16_f32 v36, v36, v37
	ds_read2_b32 v[40:41], v51 offset0:198 offset1:231
	s_waitcnt lgkmcnt(0)
	v_cvt_pk_bf16_f32 v37, v40, v41
	v_mad_i64_i32 v[42:43], s[8:9], v31, s29, v[38:39]
	ds_read2_b32 v[40:41], v51 offset0:8 offset1:41
	global_store_dwordx4 v[42:43], v[34:37], off
	v_add_u32_e32 v31, s14, v52
	v_mad_i64_i32 v[42:43], s[8:9], v31, s29, v[38:39]
	s_waitcnt lgkmcnt(0)
	v_cvt_pk_bf16_f32 v34, v40, v41
	ds_read2_b32 v[36:37], v51 offset0:74 offset1:107
	s_waitcnt lgkmcnt(0)
	v_cvt_pk_bf16_f32 v35, v36, v37
	ds_read2_b32 v[36:37], v51 offset0:140 offset1:173
	s_waitcnt lgkmcnt(0)
	v_cvt_pk_bf16_f32 v36, v36, v37
	ds_read2_b32 v[40:41], v51 offset0:206 offset1:239
	s_waitcnt lgkmcnt(0)
	v_cvt_pk_bf16_f32 v37, v40, v41
	ds_read2_b32 v[40:41], v51 offset0:16 offset1:49
	global_store_dwordx4 v[42:43], v[34:37], off
	v_add_u32_e32 v31, s14, v53
	v_mad_i64_i32 v[42:43], s[8:9], v31, s29, v[38:39]
	s_waitcnt lgkmcnt(0)
	v_cvt_pk_bf16_f32 v34, v40, v41
	ds_read2_b32 v[36:37], v51 offset0:82 offset1:115
	s_waitcnt lgkmcnt(0)
	v_cvt_pk_bf16_f32 v35, v36, v37
	ds_read2_b32 v[36:37], v51 offset0:148 offset1:181
	s_waitcnt lgkmcnt(0)
	v_cvt_pk_bf16_f32 v36, v36, v37
	ds_read2_b32 v[40:41], v51 offset0:214 offset1:247
	s_waitcnt lgkmcnt(0)
	v_cvt_pk_bf16_f32 v37, v40, v41
	ds_read2_b32 v[40:41], v51 offset0:24 offset1:57
	global_store_dwordx4 v[42:43], v[34:37], off
	v_add_u32_e32 v31, s14, v54
	v_mad_i64_i32 v[38:39], s[8:9], v31, s29, v[38:39]
	s_waitcnt lgkmcnt(0)
	v_cvt_pk_bf16_f32 v34, v40, v41
	ds_read2_b32 v[36:37], v51 offset0:90 offset1:123
	s_waitcnt lgkmcnt(0)
	v_cvt_pk_bf16_f32 v35, v36, v37
	ds_read2_b32 v[36:37], v51 offset0:156 offset1:189
	s_waitcnt lgkmcnt(0)
	v_cvt_pk_bf16_f32 v36, v36, v37
	ds_read2_b32 v[40:41], v51 offset0:222 offset1:255
	s_waitcnt lgkmcnt(0)
	v_cvt_pk_bf16_f32 v37, v40, v41
	global_store_dwordx4 v[38:39], v[34:37], off
	s_waitcnt lgkmcnt(0)
	s_mov_b64 s[14:15], 0

.LBB0_375:
	s_lshl_b32 s37, s8, 1
	s_lshl_b32 s39, s9, 1
	v_add_u32_e32 v56, s37, v36
	v_add_u32_e32 v58, s39, v31
	v_add_u32_e32 v62, s39, v33
	v_add_u32_e32 v60, s37, v38
	v_add_u32_e32 v66, s39, v37
	v_add_u32_e32 v64, s37, v40
	v_add_u32_e32 v70, s39, v39
	v_add_u32_e32 v68, s37, v42
	v_add_u32_e32 v74, s39, v41
	v_add_u32_e32 v72, s37, v44
	v_add_u32_e32 v78, s39, v43
	v_add_u32_e32 v76, s37, v46
	v_add_u32_e32 v82, s39, v45
	v_add_u32_e32 v80, s37, v48
	v_add_u32_e32 v86, s39, v47
	v_add_u32_e32 v84, s37, v50
	v_mad_i64_i32 v[56:57], s[44:45], v56, s40, v[34:35]
	v_mad_i64_i32 v[58:59], s[44:45], v58, s40, v[34:35]
	v_mad_i64_i32 v[60:61], s[44:45], v60, s40, v[34:35]
	v_mad_i64_i32 v[62:63], s[44:45], v62, s40, v[34:35]
	v_mad_i64_i32 v[64:65], s[44:45], v64, s40, v[34:35]
	v_mad_i64_i32 v[66:67], s[44:45], v66, s40, v[34:35]
	v_mad_i64_i32 v[68:69], s[44:45], v68, s40, v[34:35]
	v_mad_i64_i32 v[70:71], s[44:45], v70, s40, v[34:35]
	v_mad_i64_i32 v[72:73], s[44:45], v72, s40, v[34:35]
	v_mad_i64_i32 v[74:75], s[44:45], v74, s40, v[34:35]
	v_mad_i64_i32 v[76:77], s[44:45], v76, s40, v[34:35]
	v_mad_i64_i32 v[78:79], s[44:45], v78, s40, v[34:35]
	v_mad_i64_i32 v[80:81], s[44:45], v80, s40, v[34:35]
	v_mad_i64_i32 v[82:83], s[44:45], v82, s40, v[34:35]
	v_mad_i64_i32 v[84:85], s[44:45], v84, s40, v[34:35]
	v_mad_i64_i32 v[86:87], s[44:45], v86, s40, v[34:35]
	global_load_dword v88, v[56:57], off
	global_load_dword v89, v[58:59], off
	global_load_dword v90, v[60:61], off
	global_load_dword v91, v[62:63], off
	global_load_dword v92, v[64:65], off
	global_load_dword v93, v[66:67], off
	global_load_dword v94, v[68:69], off
	global_load_dword v95, v[70:71], off
	global_load_dword v96, v[72:73], off
	global_load_dword v97, v[74:75], off
	global_load_dword v98, v[76:77], off
	global_load_dword v99, v[78:79], off
	global_load_dword v100, v[80:81], off
	global_load_dword v101, v[82:83], off
	global_load_dword v102, v[84:85], off
	global_load_dword v103, v[86:87], off
	s_add_i32 s8, s8, 16
	s_add_i32 s9, s9, 16
	s_add_i32 s19, s19, -16
	v_add_u32_e32 v56, s37, v0
	v_add_u32_e32 v58, s39, v1
	v_add_u32_e32 v62, s39, v5
	v_add_u32_e32 v60, s37, v20
	v_add_u32_e32 v66, s39, v7
	v_add_u32_e32 v64, s37, v22
	v_add_u32_e32 v70, s39, v21
	v_add_u32_e32 v68, s37, v24
	v_add_u32_e32 v74, s39, v23
	v_add_u32_e32 v72, s37, v26
	v_add_u32_e32 v78, s39, v25
	v_add_u32_e32 v76, s37, v28
	v_add_u32_e32 v82, s39, v27
	v_add_u32_e32 v80, s37, v30
	v_add_u32_e32 v86, s39, v29
	v_add_u32_e32 v84, s37, v32
	s_cmp_lg_u32 s19, 0
	v_mad_u64_u32 v[56:57], s[44:45], v56, s16, v[4:5]
	v_mad_u64_u32 v[58:59], s[44:45], v58, s16, v[4:5]
	v_mad_u64_u32 v[60:61], s[44:45], v60, s16, v[4:5]
	v_mad_u64_u32 v[62:63], s[44:45], v62, s16, v[4:5]
	v_mad_u64_u32 v[64:65], s[44:45], v64, s16, v[4:5]
	v_mad_u64_u32 v[66:67], s[44:45], v66, s16, v[4:5]
	v_mad_u64_u32 v[68:69], s[44:45], v68, s16, v[4:5]
	v_mad_u64_u32 v[70:71], s[44:45], v70, s16, v[4:5]
	v_mad_u64_u32 v[72:73], s[44:45], v72, s16, v[4:5]
	v_mad_u64_u32 v[74:75], s[44:45], v74, s16, v[4:5]
	v_mad_u64_u32 v[76:77], s[44:45], v76, s16, v[4:5]
	v_mad_u64_u32 v[78:79], s[44:45], v78, s16, v[4:5]
	v_mad_u64_u32 v[80:81], s[44:45], v80, s16, v[4:5]
	v_mad_u64_u32 v[82:83], s[44:45], v82, s16, v[4:5]
	v_mad_u64_u32 v[84:85], s[44:45], v84, s16, v[4:5]
	v_mad_u64_u32 v[86:87], s[44:45], v86, s16, v[4:5]
	s_lshl_b32 s37, s8, 1
	s_lshl_b32 s39, s9, 1
	v_add_u32_e32 v104, s37, v36
	v_add_u32_e32 v106, s39, v31
	v_add_u32_e32 v110, s39, v33
	v_add_u32_e32 v108, s37, v38
	v_add_u32_e32 v114, s39, v37
	v_add_u32_e32 v112, s37, v40
	v_add_u32_e32 v118, s39, v39
	v_add_u32_e32 v116, s37, v42
	v_add_u32_e32 v122, s39, v41
	v_add_u32_e32 v120, s37, v44
	v_add_u32_e32 v126, s39, v43
	v_add_u32_e32 v124, s37, v46
	v_add_u32_e32 v130, s39, v45
	v_add_u32_e32 v128, s37, v48
	v_add_u32_e32 v134, s39, v47
	v_add_u32_e32 v132, s37, v50
	v_mad_i64_i32 v[104:105], s[44:45], v104, s40, v[34:35]
	v_mad_i64_i32 v[106:107], s[44:45], v106, s40, v[34:35]
	v_mad_i64_i32 v[108:109], s[44:45], v108, s40, v[34:35]
	v_mad_i64_i32 v[110:111], s[44:45], v110, s40, v[34:35]
	v_mad_i64_i32 v[112:113], s[44:45], v112, s40, v[34:35]
	v_mad_i64_i32 v[114:115], s[44:45], v114, s40, v[34:35]
	v_mad_i64_i32 v[116:117], s[44:45], v116, s40, v[34:35]
	v_mad_i64_i32 v[118:119], s[44:45], v118, s40, v[34:35]
	v_mad_i64_i32 v[120:121], s[44:45], v120, s40, v[34:35]
	v_mad_i64_i32 v[122:123], s[44:45], v122, s40, v[34:35]
	v_mad_i64_i32 v[124:125], s[44:45], v124, s40, v[34:35]
	v_mad_i64_i32 v[126:127], s[44:45], v126, s40, v[34:35]
	v_mad_i64_i32 v[128:129], s[44:45], v128, s40, v[34:35]
	v_mad_i64_i32 v[130:131], s[44:45], v130, s40, v[34:35]
	v_mad_i64_i32 v[132:133], s[44:45], v132, s40, v[34:35]
	v_mad_i64_i32 v[134:135], s[44:45], v134, s40, v[34:35]
	global_load_dword v136, v[104:105], off
	global_load_dword v137, v[106:107], off
	global_load_dword v138, v[108:109], off
	global_load_dword v139, v[110:111], off
	global_load_dword v140, v[112:113], off
	global_load_dword v141, v[114:115], off
	global_load_dword v142, v[116:117], off
	global_load_dword v143, v[118:119], off
	global_load_dword v144, v[120:121], off
	global_load_dword v145, v[122:123], off
	global_load_dword v146, v[124:125], off
	global_load_dword v147, v[126:127], off
	global_load_dword v148, v[128:129], off
	global_load_dword v149, v[130:131], off
	global_load_dword v150, v[132:133], off
	global_load_dword v151, v[134:135], off
	s_add_i32 s8, s8, 16
	s_add_i32 s9, s9, 16
	s_add_i32 s19, s19, -16
	v_add_u32_e32 v104, s37, v0
	v_add_u32_e32 v106, s39, v1
	v_add_u32_e32 v110, s39, v5
	v_add_u32_e32 v108, s37, v20
	v_add_u32_e32 v114, s39, v7
	v_add_u32_e32 v112, s37, v22
	v_add_u32_e32 v118, s39, v21
	v_add_u32_e32 v116, s37, v24
	v_add_u32_e32 v122, s39, v23
	v_add_u32_e32 v120, s37, v26
	v_add_u32_e32 v126, s39, v25
	v_add_u32_e32 v124, s37, v28
	v_add_u32_e32 v130, s39, v27
	v_add_u32_e32 v128, s37, v30
	v_add_u32_e32 v134, s39, v29
	v_add_u32_e32 v132, s37, v32
	s_cmp_lg_u32 s19, 0
	v_mad_u64_u32 v[104:105], s[44:45], v104, s16, v[4:5]
	v_mad_u64_u32 v[106:107], s[44:45], v106, s16, v[4:5]
	v_mad_u64_u32 v[108:109], s[44:45], v108, s16, v[4:5]
	v_mad_u64_u32 v[110:111], s[44:45], v110, s16, v[4:5]
	v_mad_u64_u32 v[112:113], s[44:45], v112, s16, v[4:5]
	v_mad_u64_u32 v[114:115], s[44:45], v114, s16, v[4:5]
	v_mad_u64_u32 v[116:117], s[44:45], v116, s16, v[4:5]
	v_mad_u64_u32 v[118:119], s[44:45], v118, s16, v[4:5]
	v_mad_u64_u32 v[120:121], s[44:45], v120, s16, v[4:5]
	v_mad_u64_u32 v[122:123], s[44:45], v122, s16, v[4:5]
	v_mad_u64_u32 v[124:125], s[44:45], v124, s16, v[4:5]
	v_mad_u64_u32 v[126:127], s[44:45], v126, s16, v[4:5]
	v_mad_u64_u32 v[128:129], s[44:45], v128, s16, v[4:5]
	v_mad_u64_u32 v[130:131], s[44:45], v130, s16, v[4:5]
	v_mad_u64_u32 v[132:133], s[44:45], v132, s16, v[4:5]
	v_mad_u64_u32 v[134:135], s[44:45], v134, s16, v[4:5]
	s_waitcnt vmcnt(31)
	ds_write_b32 v56, v88
	s_waitcnt vmcnt(30)
	ds_write_b32 v58, v89
	s_waitcnt vmcnt(29)
	ds_write_b32 v60, v90
	s_waitcnt vmcnt(28)
	ds_write_b32 v62, v91
	s_waitcnt vmcnt(27)
	ds_write_b32 v64, v92
	s_waitcnt vmcnt(26)
	ds_write_b32 v66, v93
	s_waitcnt vmcnt(25)
	ds_write_b32 v68, v94
	s_waitcnt vmcnt(24)
	ds_write_b32 v70, v95
	s_waitcnt vmcnt(23)
	ds_write_b32 v72, v96
	s_waitcnt vmcnt(22)
	ds_write_b32 v74, v97
	s_waitcnt vmcnt(21)
	ds_write_b32 v76, v98
	s_waitcnt vmcnt(20)
	ds_write_b32 v78, v99
	s_waitcnt vmcnt(19)
	ds_write_b32 v80, v100
	s_waitcnt vmcnt(18)
	ds_write_b32 v82, v101
	s_waitcnt vmcnt(17)
	ds_write_b32 v84, v102
	s_waitcnt vmcnt(16)
	ds_write_b32 v86, v103
	s_waitcnt vmcnt(15)
	ds_write_b32 v104, v136
	s_waitcnt vmcnt(14)
	ds_write_b32 v106, v137
	s_waitcnt vmcnt(13)
	ds_write_b32 v108, v138
	s_waitcnt vmcnt(12)
	ds_write_b32 v110, v139
	s_waitcnt vmcnt(11)
	ds_write_b32 v112, v140
	s_waitcnt vmcnt(10)
	ds_write_b32 v114, v141
	s_waitcnt vmcnt(9)
	ds_write_b32 v116, v142
	s_waitcnt vmcnt(8)
	ds_write_b32 v118, v143
	s_waitcnt vmcnt(7)
	ds_write_b32 v120, v144
	s_waitcnt vmcnt(6)
	ds_write_b32 v122, v145
	s_waitcnt vmcnt(5)
	ds_write_b32 v124, v146
	s_waitcnt vmcnt(4)
	ds_write_b32 v126, v147
	s_waitcnt vmcnt(3)
	ds_write_b32 v128, v148
	s_waitcnt vmcnt(2)
	ds_write_b32 v130, v149
	s_waitcnt vmcnt(1)
	ds_write_b32 v132, v150
	s_waitcnt vmcnt(0)
	ds_write_b32 v134, v151
	v_readlane_b32 s8, v254, 44
	s_add_u32 s0, s8, s0
	v_readlane_b32 s8, v254, 46
	s_addc_u32 s19, s8, 0
	s_lshl_b32 s8, s18, 6
	s_waitcnt lgkmcnt(0)
	s_and_b32 s8, s8, 0xffffff00
	s_and_b32 s9, s38, 0x60
	s_or_b32 s18, s8, s9
	ds_read2_b32 v[34:35], v51 offset1:33
	s_or_b32 s37, s18, 0x80
	s_waitcnt lgkmcnt(0)
	v_cvt_pk_bf16_f32 v34, v34, v35
	ds_read2_b32 v[36:37], v51 offset0:66 offset1:99
	s_and_b64 s[8:9], s[14:15], exec
	s_waitcnt lgkmcnt(0)
	v_cvt_pk_bf16_f32 v35, v36, v37
	ds_read2_b32 v[36:37], v51 offset0:132 offset1:165
	s_cselect_b32 s14, s18, s37
	s_ashr_i32 s37, s36, 31
	s_lshl_b64 s[8:9], s[36:37], 1
	s_waitcnt lgkmcnt(0)
	v_cvt_pk_bf16_f32 v36, v36, v37
	ds_read2_b32 v[38:39], v51 offset0:198 offset1:231
	s_add_u32 s8, s0, s8
	s_waitcnt lgkmcnt(0)
	v_cvt_pk_bf16_f32 v37, v38, v39
	v_add_u32_e32 v38, s14, v49
	s_addc_u32 s9, s19, s9
	v_lshlrev_b32_e32 v40, 1, v6
	v_mov_b32_e32 v41, v3
	v_ashrrev_i32_e32 v39, 31, v38
	v_lshl_add_u64 v[40:41], s[8:9], 0, v[40:41]
	v_lshlrev_b64 v[38:39], 11, v[38:39]
	ds_read2_b32 v[42:43], v51 offset0:8 offset1:41
	v_lshl_add_u64 v[38:39], v[40:41], 0, v[38:39]
	global_store_dwordx4 v[38:39], v[34:37], off
	s_waitcnt lgkmcnt(0)
	s_nop 0
	v_cvt_pk_bf16_f32 v34, v42, v43
	v_add_u32_e32 v42, s14, v52
	v_ashrrev_i32_e32 v43, 31, v42
	ds_read2_b32 v[36:37], v51 offset0:74 offset1:107
	v_lshlrev_b64 v[42:43], 11, v[42:43]
	s_waitcnt lgkmcnt(0)
	v_cvt_pk_bf16_f32 v35, v36, v37
	ds_read2_b32 v[36:37], v51 offset0:140 offset1:173
	v_lshl_add_u64 v[42:43], v[40:41], 0, v[42:43]
	s_waitcnt lgkmcnt(0)
	v_cvt_pk_bf16_f32 v36, v36, v37
	ds_read2_b32 v[38:39], v51 offset0:206 offset1:239
	s_waitcnt lgkmcnt(0)
	v_cvt_pk_bf16_f32 v37, v38, v39
	global_store_dwordx4 v[42:43], v[34:37], off
	v_add_u32_e32 v42, s14, v53
	ds_read2_b32 v[38:39], v51 offset0:16 offset1:49
	s_waitcnt lgkmcnt(0)
	v_cvt_pk_bf16_f32 v34, v38, v39
	ds_read2_b32 v[36:37], v51 offset0:82 offset1:115
	v_ashrrev_i32_e32 v43, 31, v42
	s_waitcnt lgkmcnt(0)
	v_cvt_pk_bf16_f32 v35, v36, v37
	ds_read2_b32 v[36:37], v51 offset0:148 offset1:181
	v_lshlrev_b64 v[42:43], 11, v[42:43]
	s_waitcnt lgkmcnt(0)
	v_cvt_pk_bf16_f32 v36, v36, v37
	ds_read2_b32 v[38:39], v51 offset0:214 offset1:247
	s_waitcnt lgkmcnt(0)
	v_cvt_pk_bf16_f32 v37, v38, v39
	v_lshl_add_u64 v[42:43], v[40:41], 0, v[42:43]
	ds_read2_b32 v[38:39], v51 offset0:24 offset1:57
	global_store_dwordx4 v[42:43], v[34:37], off
	v_add_u32_e32 v42, s14, v54
	v_ashrrev_i32_e32 v43, 31, v42
	s_waitcnt lgkmcnt(0)
	v_cvt_pk_bf16_f32 v34, v38, v39
	ds_read2_b32 v[36:37], v51 offset0:90 offset1:123
	s_waitcnt lgkmcnt(0)
	v_cvt_pk_bf16_f32 v35, v36, v37
	ds_read2_b32 v[36:37], v51 offset0:156 offset1:189
	s_waitcnt lgkmcnt(0)
	v_cvt_pk_bf16_f32 v36, v36, v37
	ds_read2_b32 v[38:39], v51 offset0:222 offset1:255
	v_lshlrev_b64 v[42:43], 11, v[42:43]
	s_waitcnt lgkmcnt(0)
	v_cvt_pk_bf16_f32 v37, v38, v39
	v_lshl_add_u64 v[38:39], v[40:41], 0, v[42:43]
	global_store_dwordx4 v[38:39], v[34:37], off
	s_waitcnt lgkmcnt(0)

.LBB0_380:
	s_lshl_b32 s8, s18, 1
	s_lshl_b32 s9, s15, 1
	v_add_u32_e32 v58, s8, v36
	v_add_u32_e32 v56, s9, v31
	v_add_u32_e32 v60, s9, v33
	v_add_u32_e32 v62, s8, v38
	v_add_u32_e32 v64, s9, v37
	v_add_u32_e32 v66, s8, v40
	v_add_u32_e32 v68, s9, v39
	v_add_u32_e32 v70, s8, v42
	v_add_u32_e32 v72, s9, v41
	v_add_u32_e32 v74, s8, v44
	v_add_u32_e32 v76, s9, v43
	v_add_u32_e32 v78, s8, v46
	v_add_u32_e32 v80, s9, v45
	v_add_u32_e32 v82, s8, v48
	v_add_u32_e32 v84, s9, v47
	v_add_u32_e32 v86, s8, v50
	v_ashrrev_i32_e32 v59, 31, v58
	v_ashrrev_i32_e32 v57, 31, v56
	v_ashrrev_i32_e32 v63, 31, v62
	v_ashrrev_i32_e32 v61, 31, v60
	v_ashrrev_i32_e32 v67, 31, v66
	v_ashrrev_i32_e32 v65, 31, v64
	v_ashrrev_i32_e32 v71, 31, v70
	v_ashrrev_i32_e32 v69, 31, v68
	v_ashrrev_i32_e32 v75, 31, v74
	v_ashrrev_i32_e32 v73, 31, v72
	v_ashrrev_i32_e32 v79, 31, v78
	v_ashrrev_i32_e32 v77, 31, v76
	v_ashrrev_i32_e32 v83, 31, v82
	v_ashrrev_i32_e32 v81, 31, v80
	v_ashrrev_i32_e32 v87, 31, v86
	v_ashrrev_i32_e32 v85, 31, v84
	v_lshlrev_b64 v[58:59], 12, v[58:59]
	v_lshlrev_b64 v[56:57], 12, v[56:57]
	v_lshlrev_b64 v[60:61], 12, v[60:61]
	v_lshlrev_b64 v[62:63], 12, v[62:63]
	v_lshlrev_b64 v[64:65], 12, v[64:65]
	v_lshlrev_b64 v[66:67], 12, v[66:67]
	v_lshlrev_b64 v[68:69], 12, v[68:69]
	v_lshlrev_b64 v[70:71], 12, v[70:71]
	v_lshlrev_b64 v[72:73], 12, v[72:73]
	v_lshlrev_b64 v[74:75], 12, v[74:75]
	v_lshlrev_b64 v[76:77], 12, v[76:77]
	v_lshlrev_b64 v[78:79], 12, v[78:79]
	v_lshlrev_b64 v[80:81], 12, v[80:81]
	v_lshlrev_b64 v[82:83], 12, v[82:83]
	v_lshlrev_b64 v[84:85], 12, v[84:85]
	v_lshlrev_b64 v[86:87], 12, v[86:87]
	v_lshl_add_u64 v[58:59], v[34:35], 0, v[58:59]
	v_lshl_add_u64 v[56:57], v[34:35], 0, v[56:57]
	v_lshl_add_u64 v[62:63], v[34:35], 0, v[62:63]
	v_lshl_add_u64 v[60:61], v[34:35], 0, v[60:61]
	v_lshl_add_u64 v[66:67], v[34:35], 0, v[66:67]
	v_lshl_add_u64 v[64:65], v[34:35], 0, v[64:65]
	v_lshl_add_u64 v[70:71], v[34:35], 0, v[70:71]
	v_lshl_add_u64 v[68:69], v[34:35], 0, v[68:69]
	v_lshl_add_u64 v[74:75], v[34:35], 0, v[74:75]
	v_lshl_add_u64 v[72:73], v[34:35], 0, v[72:73]
	v_lshl_add_u64 v[78:79], v[34:35], 0, v[78:79]
	v_lshl_add_u64 v[76:77], v[34:35], 0, v[76:77]
	v_lshl_add_u64 v[82:83], v[34:35], 0, v[82:83]
	v_lshl_add_u64 v[80:81], v[34:35], 0, v[80:81]
	v_lshl_add_u64 v[86:87], v[34:35], 0, v[86:87]
	v_lshl_add_u64 v[84:85], v[34:35], 0, v[84:85]
	global_load_dword v88, v[58:59], off
	global_load_dword v89, v[56:57], off
	global_load_dword v90, v[62:63], off
	global_load_dword v91, v[60:61], off
	global_load_dword v92, v[66:67], off
	global_load_dword v93, v[64:65], off
	global_load_dword v94, v[70:71], off
	global_load_dword v95, v[68:69], off
	global_load_dword v96, v[74:75], off
	global_load_dword v97, v[72:73], off
	global_load_dword v98, v[78:79], off
	global_load_dword v99, v[76:77], off
	global_load_dword v100, v[82:83], off
	global_load_dword v101, v[80:81], off
	global_load_dword v102, v[86:87], off
	global_load_dword v103, v[84:85], off
	s_add_i32 s18, s18, 16
	s_add_i32 s15, s15, 16
	s_add_i32 s19, s19, -16
	v_add_u32_e32 v56, s8, v0
	v_add_u32_e32 v58, s9, v1
	v_add_u32_e32 v62, s9, v5
	v_add_u32_e32 v60, s8, v20
	v_add_u32_e32 v66, s9, v7
	v_add_u32_e32 v64, s8, v22
	v_add_u32_e32 v70, s9, v21
	v_add_u32_e32 v68, s8, v24
	v_add_u32_e32 v74, s9, v23
	v_add_u32_e32 v72, s8, v26
	v_add_u32_e32 v78, s9, v25
	v_add_u32_e32 v76, s8, v28
	v_add_u32_e32 v82, s9, v27
	v_add_u32_e32 v80, s8, v30
	v_add_u32_e32 v86, s9, v29
	v_add_u32_e32 v84, s8, v32
	s_cmp_lg_u32 s19, 0
	v_mad_u64_u32 v[56:57], s[8:9], v56, s16, v[4:5]
	v_mad_u64_u32 v[58:59], s[8:9], v58, s16, v[4:5]
	v_mad_u64_u32 v[60:61], s[8:9], v60, s16, v[4:5]
	v_mad_u64_u32 v[62:63], s[8:9], v62, s16, v[4:5]
	v_mad_u64_u32 v[64:65], s[8:9], v64, s16, v[4:5]
	v_mad_u64_u32 v[66:67], s[8:9], v66, s16, v[4:5]
	v_mad_u64_u32 v[68:69], s[8:9], v68, s16, v[4:5]
	v_mad_u64_u32 v[70:71], s[8:9], v70, s16, v[4:5]
	v_mad_u64_u32 v[72:73], s[8:9], v72, s16, v[4:5]
	v_mad_u64_u32 v[74:75], s[8:9], v74, s16, v[4:5]
	v_mad_u64_u32 v[76:77], s[8:9], v76, s16, v[4:5]
	v_mad_u64_u32 v[78:79], s[8:9], v78, s16, v[4:5]
	v_mad_u64_u32 v[80:81], s[8:9], v80, s16, v[4:5]
	v_mad_u64_u32 v[82:83], s[8:9], v82, s16, v[4:5]
	v_mad_u64_u32 v[84:85], s[8:9], v84, s16, v[4:5]
	v_mad_u64_u32 v[86:87], s[8:9], v86, s16, v[4:5]
	s_lshl_b32 s8, s18, 1
	s_lshl_b32 s9, s15, 1
	v_add_u32_e32 v106, s8, v36
	v_add_u32_e32 v104, s9, v31
	v_add_u32_e32 v108, s9, v33
	v_add_u32_e32 v110, s8, v38
	v_add_u32_e32 v112, s9, v37
	v_add_u32_e32 v114, s8, v40
	v_add_u32_e32 v116, s9, v39
	v_add_u32_e32 v118, s8, v42
	v_add_u32_e32 v120, s9, v41
	v_add_u32_e32 v122, s8, v44
	v_add_u32_e32 v124, s9, v43
	v_add_u32_e32 v126, s8, v46
	v_add_u32_e32 v128, s9, v45
	v_add_u32_e32 v130, s8, v48
	v_add_u32_e32 v132, s9, v47
	v_add_u32_e32 v134, s8, v50
	v_ashrrev_i32_e32 v107, 31, v106
	v_ashrrev_i32_e32 v105, 31, v104
	v_ashrrev_i32_e32 v111, 31, v110
	v_ashrrev_i32_e32 v109, 31, v108
	v_ashrrev_i32_e32 v115, 31, v114
	v_ashrrev_i32_e32 v113, 31, v112
	v_ashrrev_i32_e32 v119, 31, v118
	v_ashrrev_i32_e32 v117, 31, v116
	v_ashrrev_i32_e32 v123, 31, v122
	v_ashrrev_i32_e32 v121, 31, v120
	v_ashrrev_i32_e32 v127, 31, v126
	v_ashrrev_i32_e32 v125, 31, v124
	v_ashrrev_i32_e32 v131, 31, v130
	v_ashrrev_i32_e32 v129, 31, v128
	v_ashrrev_i32_e32 v135, 31, v134
	v_ashrrev_i32_e32 v133, 31, v132
	v_lshlrev_b64 v[106:107], 12, v[106:107]
	v_lshlrev_b64 v[104:105], 12, v[104:105]
	v_lshlrev_b64 v[108:109], 12, v[108:109]
	v_lshlrev_b64 v[110:111], 12, v[110:111]
	v_lshlrev_b64 v[112:113], 12, v[112:113]
	v_lshlrev_b64 v[114:115], 12, v[114:115]
	v_lshlrev_b64 v[116:117], 12, v[116:117]
	v_lshlrev_b64 v[118:119], 12, v[118:119]
	v_lshlrev_b64 v[120:121], 12, v[120:121]
	v_lshlrev_b64 v[122:123], 12, v[122:123]
	v_lshlrev_b64 v[124:125], 12, v[124:125]
	v_lshlrev_b64 v[126:127], 12, v[126:127]
	v_lshlrev_b64 v[128:129], 12, v[128:129]
	v_lshlrev_b64 v[130:131], 12, v[130:131]
	v_lshlrev_b64 v[132:133], 12, v[132:133]
	v_lshlrev_b64 v[134:135], 12, v[134:135]
	v_lshl_add_u64 v[106:107], v[34:35], 0, v[106:107]
	v_lshl_add_u64 v[104:105], v[34:35], 0, v[104:105]
	v_lshl_add_u64 v[110:111], v[34:35], 0, v[110:111]
	v_lshl_add_u64 v[108:109], v[34:35], 0, v[108:109]
	v_lshl_add_u64 v[114:115], v[34:35], 0, v[114:115]
	v_lshl_add_u64 v[112:113], v[34:35], 0, v[112:113]
	v_lshl_add_u64 v[118:119], v[34:35], 0, v[118:119]
	v_lshl_add_u64 v[116:117], v[34:35], 0, v[116:117]
	v_lshl_add_u64 v[122:123], v[34:35], 0, v[122:123]
	v_lshl_add_u64 v[120:121], v[34:35], 0, v[120:121]
	v_lshl_add_u64 v[126:127], v[34:35], 0, v[126:127]
	v_lshl_add_u64 v[124:125], v[34:35], 0, v[124:125]
	v_lshl_add_u64 v[130:131], v[34:35], 0, v[130:131]
	v_lshl_add_u64 v[128:129], v[34:35], 0, v[128:129]
	v_lshl_add_u64 v[134:135], v[34:35], 0, v[134:135]
	v_lshl_add_u64 v[132:133], v[34:35], 0, v[132:133]
	global_load_dword v136, v[106:107], off
	global_load_dword v137, v[104:105], off
	global_load_dword v138, v[110:111], off
	global_load_dword v139, v[108:109], off
	global_load_dword v140, v[114:115], off
	global_load_dword v141, v[112:113], off
	global_load_dword v142, v[118:119], off
	global_load_dword v143, v[116:117], off
	global_load_dword v144, v[122:123], off
	global_load_dword v145, v[120:121], off
	global_load_dword v146, v[126:127], off
	global_load_dword v147, v[124:125], off
	global_load_dword v148, v[130:131], off
	global_load_dword v149, v[128:129], off
	global_load_dword v150, v[134:135], off
	global_load_dword v151, v[132:133], off
	s_add_i32 s18, s18, 16
	s_add_i32 s15, s15, 16
	s_add_i32 s19, s19, -16
	v_add_u32_e32 v104, s8, v0
	v_add_u32_e32 v106, s9, v1
	v_add_u32_e32 v110, s9, v5
	v_add_u32_e32 v108, s8, v20
	v_add_u32_e32 v114, s9, v7
	v_add_u32_e32 v112, s8, v22
	v_add_u32_e32 v118, s9, v21
	v_add_u32_e32 v116, s8, v24
	v_add_u32_e32 v122, s9, v23
	v_add_u32_e32 v120, s8, v26
	v_add_u32_e32 v126, s9, v25
	v_add_u32_e32 v124, s8, v28
	v_add_u32_e32 v130, s9, v27
	v_add_u32_e32 v128, s8, v30
	v_add_u32_e32 v134, s9, v29
	v_add_u32_e32 v132, s8, v32
	s_cmp_lg_u32 s19, 0
	v_mad_u64_u32 v[104:105], s[8:9], v104, s16, v[4:5]
	v_mad_u64_u32 v[106:107], s[8:9], v106, s16, v[4:5]
	v_mad_u64_u32 v[108:109], s[8:9], v108, s16, v[4:5]
	v_mad_u64_u32 v[110:111], s[8:9], v110, s16, v[4:5]
	v_mad_u64_u32 v[112:113], s[8:9], v112, s16, v[4:5]
	v_mad_u64_u32 v[114:115], s[8:9], v114, s16, v[4:5]
	v_mad_u64_u32 v[116:117], s[8:9], v116, s16, v[4:5]
	v_mad_u64_u32 v[118:119], s[8:9], v118, s16, v[4:5]
	v_mad_u64_u32 v[120:121], s[8:9], v120, s16, v[4:5]
	v_mad_u64_u32 v[122:123], s[8:9], v122, s16, v[4:5]
	v_mad_u64_u32 v[124:125], s[8:9], v124, s16, v[4:5]
	v_mad_u64_u32 v[126:127], s[8:9], v126, s16, v[4:5]
	v_mad_u64_u32 v[128:129], s[8:9], v128, s16, v[4:5]
	v_mad_u64_u32 v[130:131], s[8:9], v130, s16, v[4:5]
	v_mad_u64_u32 v[132:133], s[8:9], v132, s16, v[4:5]
	v_mad_u64_u32 v[134:135], s[8:9], v134, s16, v[4:5]
	s_waitcnt vmcnt(31)
	ds_write_b32 v56, v88
	s_waitcnt vmcnt(30)
	ds_write_b32 v58, v89
	s_waitcnt vmcnt(29)
	ds_write_b32 v60, v90
	s_waitcnt vmcnt(28)
	ds_write_b32 v62, v91
	s_waitcnt vmcnt(27)
	ds_write_b32 v64, v92
	s_waitcnt vmcnt(26)
	ds_write_b32 v66, v93
	s_waitcnt vmcnt(25)
	ds_write_b32 v68, v94
	s_waitcnt vmcnt(24)
	ds_write_b32 v70, v95
	s_waitcnt vmcnt(23)
	ds_write_b32 v72, v96
	s_waitcnt vmcnt(22)
	ds_write_b32 v74, v97
	s_waitcnt vmcnt(21)
	ds_write_b32 v76, v98
	s_waitcnt vmcnt(20)
	ds_write_b32 v78, v99
	s_waitcnt vmcnt(19)
	ds_write_b32 v80, v100
	s_waitcnt vmcnt(18)
	ds_write_b32 v82, v101
	s_waitcnt vmcnt(17)
	ds_write_b32 v84, v102
	s_waitcnt vmcnt(16)
	ds_write_b32 v86, v103
	s_waitcnt vmcnt(15)
	ds_write_b32 v104, v136
	s_waitcnt vmcnt(14)
	ds_write_b32 v106, v137
	s_waitcnt vmcnt(13)
	ds_write_b32 v108, v138
	s_waitcnt vmcnt(12)
	ds_write_b32 v110, v139
	s_waitcnt vmcnt(11)
	ds_write_b32 v112, v140
	s_waitcnt vmcnt(10)
	ds_write_b32 v114, v141
	s_waitcnt vmcnt(9)
	ds_write_b32 v116, v142
	s_waitcnt vmcnt(8)
	ds_write_b32 v118, v143
	s_waitcnt vmcnt(7)
	ds_write_b32 v120, v144
	s_waitcnt vmcnt(6)
	ds_write_b32 v122, v145
	s_waitcnt vmcnt(5)
	ds_write_b32 v124, v146
	s_waitcnt vmcnt(4)
	ds_write_b32 v126, v147
	s_waitcnt vmcnt(3)
	ds_write_b32 v128, v148
	s_waitcnt vmcnt(2)
	ds_write_b32 v130, v149
	s_waitcnt vmcnt(1)
	ds_write_b32 v132, v150
	s_waitcnt vmcnt(0)
	ds_write_b32 v134, v151
	s_waitcnt lgkmcnt(0)
	v_add_u32_e32 v40, s14, v49
	ds_read2_b32 v[34:35], v51 offset1:33
	s_lshl_b32 s0, s0, 1
	v_ashrrev_i32_e32 v41, 31, v40
	s_waitcnt lgkmcnt(0)
	v_cvt_pk_bf16_f32 v34, v34, v35
	ds_read2_b32 v[36:37], v51 offset0:66 offset1:99
	v_lshl_add_u64 v[42:43], v[10:11], 0, s[0:1]
	v_lshlrev_b64 v[40:41], 11, v[40:41]
	s_waitcnt lgkmcnt(0)
	v_cvt_pk_bf16_f32 v35, v36, v37
	ds_read2_b32 v[36:37], v51 offset0:132 offset1:165
	v_lshl_add_u64 v[40:41], v[42:43], 0, v[40:41]
	s_waitcnt lgkmcnt(0)
	v_cvt_pk_bf16_f32 v36, v36, v37
	ds_read2_b32 v[38:39], v51 offset0:198 offset1:231
	s_waitcnt lgkmcnt(0)
	v_cvt_pk_bf16_f32 v37, v38, v39
	global_store_dwordx4 v[40:41], v[34:37], off
	v_add_u32_e32 v40, s14, v52
	v_ashrrev_i32_e32 v41, 31, v40
	ds_read2_b32 v[38:39], v51 offset0:8 offset1:41
	s_waitcnt lgkmcnt(0)
	v_cvt_pk_bf16_f32 v34, v38, v39
	ds_read2_b32 v[36:37], v51 offset0:74 offset1:107
	v_lshlrev_b64 v[40:41], 11, v[40:41]
	s_waitcnt lgkmcnt(0)
	v_cvt_pk_bf16_f32 v35, v36, v37
	ds_read2_b32 v[36:37], v51 offset0:140 offset1:173
	v_lshl_add_u64 v[40:41], v[42:43], 0, v[40:41]
	s_waitcnt lgkmcnt(0)
	v_cvt_pk_bf16_f32 v36, v36, v37
	ds_read2_b32 v[38:39], v51 offset0:206 offset1:239
	s_waitcnt lgkmcnt(0)
	v_cvt_pk_bf16_f32 v37, v38, v39
	global_store_dwordx4 v[40:41], v[34:37], off
	v_add_u32_e32 v40, s14, v53
	ds_read2_b32 v[38:39], v51 offset0:16 offset1:49
	s_waitcnt lgkmcnt(0)
	v_cvt_pk_bf16_f32 v34, v38, v39
	ds_read2_b32 v[36:37], v51 offset0:82 offset1:115
	v_ashrrev_i32_e32 v41, 31, v40
	s_waitcnt lgkmcnt(0)
	v_cvt_pk_bf16_f32 v35, v36, v37
	ds_read2_b32 v[36:37], v51 offset0:148 offset1:181
	v_lshlrev_b64 v[40:41], 11, v[40:41]
	s_waitcnt lgkmcnt(0)
	v_cvt_pk_bf16_f32 v36, v36, v37
	ds_read2_b32 v[38:39], v51 offset0:214 offset1:247
	s_waitcnt lgkmcnt(0)
	v_cvt_pk_bf16_f32 v37, v38, v39
	v_lshl_add_u64 v[40:41], v[42:43], 0, v[40:41]
	ds_read2_b32 v[38:39], v51 offset0:24 offset1:57
	global_store_dwordx4 v[40:41], v[34:37], off
	v_add_u32_e32 v40, s14, v54
	v_ashrrev_i32_e32 v41, 31, v40
	s_waitcnt lgkmcnt(0)
	v_cvt_pk_bf16_f32 v34, v38, v39
	ds_read2_b32 v[36:37], v51 offset0:90 offset1:123
	s_waitcnt lgkmcnt(0)
	v_cvt_pk_bf16_f32 v35, v36, v37
	ds_read2_b32 v[36:37], v51 offset0:156 offset1:189
	s_waitcnt lgkmcnt(0)
	v_cvt_pk_bf16_f32 v36, v36, v37
	ds_read2_b32 v[38:39], v51 offset0:222 offset1:255
	v_lshlrev_b64 v[40:41], 11, v[40:41]
	s_waitcnt lgkmcnt(0)
	v_cvt_pk_bf16_f32 v37, v38, v39
	v_lshl_add_u64 v[38:39], v[42:43], 0, v[40:41]
	global_store_dwordx4 v[38:39], v[34:37], off
	s_waitcnt lgkmcnt(0)

.LBB0_385:
	s_lshl_b32 s19, s15, 1
	s_lshl_b32 s38, s9, 1
	v_add_u32_e32 v56, s19, v36
	v_add_u32_e32 v58, s38, v31
	v_add_u32_e32 v62, s38, v33
	v_add_u32_e32 v60, s19, v38
	v_add_u32_e32 v66, s38, v37
	v_add_u32_e32 v64, s19, v40
	v_add_u32_e32 v70, s38, v39
	v_add_u32_e32 v68, s19, v42
	v_add_u32_e32 v74, s38, v41
	v_add_u32_e32 v72, s19, v44
	v_add_u32_e32 v78, s38, v43
	v_add_u32_e32 v76, s19, v46
	v_add_u32_e32 v82, s38, v45
	v_add_u32_e32 v80, s19, v48
	v_add_u32_e32 v86, s38, v47
	v_add_u32_e32 v84, s19, v50
	v_mad_i64_i32 v[56:57], s[36:37], v56, s41, v[34:35]
	v_mad_i64_i32 v[58:59], s[36:37], v58, s41, v[34:35]
	v_mad_i64_i32 v[60:61], s[36:37], v60, s41, v[34:35]
	v_mad_i64_i32 v[62:63], s[36:37], v62, s41, v[34:35]
	v_mad_i64_i32 v[64:65], s[36:37], v64, s41, v[34:35]
	v_mad_i64_i32 v[66:67], s[36:37], v66, s41, v[34:35]
	v_mad_i64_i32 v[68:69], s[36:37], v68, s41, v[34:35]
	v_mad_i64_i32 v[70:71], s[36:37], v70, s41, v[34:35]
	v_mad_i64_i32 v[72:73], s[36:37], v72, s41, v[34:35]
	v_mad_i64_i32 v[74:75], s[36:37], v74, s41, v[34:35]
	v_mad_i64_i32 v[76:77], s[36:37], v76, s41, v[34:35]
	v_mad_i64_i32 v[78:79], s[36:37], v78, s41, v[34:35]
	v_mad_i64_i32 v[80:81], s[36:37], v80, s41, v[34:35]
	v_mad_i64_i32 v[82:83], s[36:37], v82, s41, v[34:35]
	v_mad_i64_i32 v[84:85], s[36:37], v84, s41, v[34:35]
	v_mad_i64_i32 v[86:87], s[36:37], v86, s41, v[34:35]
	global_load_dword v88, v[56:57], off
	global_load_dword v89, v[58:59], off
	global_load_dword v90, v[60:61], off
	global_load_dword v91, v[62:63], off
	global_load_dword v92, v[64:65], off
	global_load_dword v93, v[66:67], off
	global_load_dword v94, v[68:69], off
	global_load_dword v95, v[70:71], off
	global_load_dword v96, v[72:73], off
	global_load_dword v97, v[74:75], off
	global_load_dword v98, v[76:77], off
	global_load_dword v99, v[78:79], off
	global_load_dword v100, v[80:81], off
	global_load_dword v101, v[82:83], off
	global_load_dword v102, v[84:85], off
	global_load_dword v103, v[86:87], off
	s_add_i32 s15, s15, 16
	s_add_i32 s9, s9, 16
	s_add_i32 s18, s18, -16
	v_add_u32_e32 v56, s19, v0
	v_add_u32_e32 v58, s38, v1
	v_add_u32_e32 v62, s38, v5
	v_add_u32_e32 v60, s19, v20
	v_add_u32_e32 v66, s38, v7
	v_add_u32_e32 v64, s19, v22
	v_add_u32_e32 v70, s38, v21
	v_add_u32_e32 v68, s19, v24
	v_add_u32_e32 v74, s38, v23
	v_add_u32_e32 v72, s19, v26
	v_add_u32_e32 v78, s38, v25
	v_add_u32_e32 v76, s19, v28
	v_add_u32_e32 v82, s38, v27
	v_add_u32_e32 v80, s19, v30
	v_add_u32_e32 v86, s38, v29
	v_add_u32_e32 v84, s19, v32
	s_cmp_lg_u32 s18, 0
	v_mad_u64_u32 v[56:57], s[36:37], v56, s16, v[4:5]
	v_mad_u64_u32 v[58:59], s[36:37], v58, s16, v[4:5]
	v_mad_u64_u32 v[60:61], s[36:37], v60, s16, v[4:5]
	v_mad_u64_u32 v[62:63], s[36:37], v62, s16, v[4:5]
	v_mad_u64_u32 v[64:65], s[36:37], v64, s16, v[4:5]
	v_mad_u64_u32 v[66:67], s[36:37], v66, s16, v[4:5]
	v_mad_u64_u32 v[68:69], s[36:37], v68, s16, v[4:5]
	v_mad_u64_u32 v[70:71], s[36:37], v70, s16, v[4:5]
	v_mad_u64_u32 v[72:73], s[36:37], v72, s16, v[4:5]
	v_mad_u64_u32 v[74:75], s[36:37], v74, s16, v[4:5]
	v_mad_u64_u32 v[76:77], s[36:37], v76, s16, v[4:5]
	v_mad_u64_u32 v[78:79], s[36:37], v78, s16, v[4:5]
	v_mad_u64_u32 v[80:81], s[36:37], v80, s16, v[4:5]
	v_mad_u64_u32 v[82:83], s[36:37], v82, s16, v[4:5]
	v_mad_u64_u32 v[84:85], s[36:37], v84, s16, v[4:5]
	v_mad_u64_u32 v[86:87], s[36:37], v86, s16, v[4:5]
	s_lshl_b32 s19, s15, 1
	s_lshl_b32 s38, s9, 1
	v_add_u32_e32 v104, s19, v36
	v_add_u32_e32 v106, s38, v31
	v_add_u32_e32 v110, s38, v33
	v_add_u32_e32 v108, s19, v38
	v_add_u32_e32 v114, s38, v37
	v_add_u32_e32 v112, s19, v40
	v_add_u32_e32 v118, s38, v39
	v_add_u32_e32 v116, s19, v42
	v_add_u32_e32 v122, s38, v41
	v_add_u32_e32 v120, s19, v44
	v_add_u32_e32 v126, s38, v43
	v_add_u32_e32 v124, s19, v46
	v_add_u32_e32 v130, s38, v45
	v_add_u32_e32 v128, s19, v48
	v_add_u32_e32 v134, s38, v47
	v_add_u32_e32 v132, s19, v50
	v_mad_i64_i32 v[104:105], s[36:37], v104, s41, v[34:35]
	v_mad_i64_i32 v[106:107], s[36:37], v106, s41, v[34:35]
	v_mad_i64_i32 v[108:109], s[36:37], v108, s41, v[34:35]
	v_mad_i64_i32 v[110:111], s[36:37], v110, s41, v[34:35]
	v_mad_i64_i32 v[112:113], s[36:37], v112, s41, v[34:35]
	v_mad_i64_i32 v[114:115], s[36:37], v114, s41, v[34:35]
	v_mad_i64_i32 v[116:117], s[36:37], v116, s41, v[34:35]
	v_mad_i64_i32 v[118:119], s[36:37], v118, s41, v[34:35]
	v_mad_i64_i32 v[120:121], s[36:37], v120, s41, v[34:35]
	v_mad_i64_i32 v[122:123], s[36:37], v122, s41, v[34:35]
	v_mad_i64_i32 v[124:125], s[36:37], v124, s41, v[34:35]
	v_mad_i64_i32 v[126:127], s[36:37], v126, s41, v[34:35]
	v_mad_i64_i32 v[128:129], s[36:37], v128, s41, v[34:35]
	v_mad_i64_i32 v[130:131], s[36:37], v130, s41, v[34:35]
	v_mad_i64_i32 v[132:133], s[36:37], v132, s41, v[34:35]
	v_mad_i64_i32 v[134:135], s[36:37], v134, s41, v[34:35]
	global_load_dword v136, v[104:105], off
	global_load_dword v137, v[106:107], off
	global_load_dword v138, v[108:109], off
	global_load_dword v139, v[110:111], off
	global_load_dword v140, v[112:113], off
	global_load_dword v141, v[114:115], off
	global_load_dword v142, v[116:117], off
	global_load_dword v143, v[118:119], off
	global_load_dword v144, v[120:121], off
	global_load_dword v145, v[122:123], off
	global_load_dword v146, v[124:125], off
	global_load_dword v147, v[126:127], off
	global_load_dword v148, v[128:129], off
	global_load_dword v149, v[130:131], off
	global_load_dword v150, v[132:133], off
	global_load_dword v151, v[134:135], off
	s_add_i32 s15, s15, 16
	s_add_i32 s9, s9, 16
	s_add_i32 s18, s18, -16
	v_add_u32_e32 v104, s19, v0
	v_add_u32_e32 v106, s38, v1
	v_add_u32_e32 v110, s38, v5
	v_add_u32_e32 v108, s19, v20
	v_add_u32_e32 v114, s38, v7
	v_add_u32_e32 v112, s19, v22
	v_add_u32_e32 v118, s38, v21
	v_add_u32_e32 v116, s19, v24
	v_add_u32_e32 v122, s38, v23
	v_add_u32_e32 v120, s19, v26
	v_add_u32_e32 v126, s38, v25
	v_add_u32_e32 v124, s19, v28
	v_add_u32_e32 v130, s38, v27
	v_add_u32_e32 v128, s19, v30
	v_add_u32_e32 v134, s38, v29
	v_add_u32_e32 v132, s19, v32
	s_cmp_lg_u32 s18, 0
	v_mad_u64_u32 v[104:105], s[36:37], v104, s16, v[4:5]
	v_mad_u64_u32 v[106:107], s[36:37], v106, s16, v[4:5]
	v_mad_u64_u32 v[108:109], s[36:37], v108, s16, v[4:5]
	v_mad_u64_u32 v[110:111], s[36:37], v110, s16, v[4:5]
	v_mad_u64_u32 v[112:113], s[36:37], v112, s16, v[4:5]
	v_mad_u64_u32 v[114:115], s[36:37], v114, s16, v[4:5]
	v_mad_u64_u32 v[116:117], s[36:37], v116, s16, v[4:5]
	v_mad_u64_u32 v[118:119], s[36:37], v118, s16, v[4:5]
	v_mad_u64_u32 v[120:121], s[36:37], v120, s16, v[4:5]
	v_mad_u64_u32 v[122:123], s[36:37], v122, s16, v[4:5]
	v_mad_u64_u32 v[124:125], s[36:37], v124, s16, v[4:5]
	v_mad_u64_u32 v[126:127], s[36:37], v126, s16, v[4:5]
	v_mad_u64_u32 v[128:129], s[36:37], v128, s16, v[4:5]
	v_mad_u64_u32 v[130:131], s[36:37], v130, s16, v[4:5]
	v_mad_u64_u32 v[132:133], s[36:37], v132, s16, v[4:5]
	v_mad_u64_u32 v[134:135], s[36:37], v134, s16, v[4:5]
	s_waitcnt vmcnt(31)
	ds_write_b32 v56, v88
	s_waitcnt vmcnt(30)
	ds_write_b32 v58, v89
	s_waitcnt vmcnt(29)
	ds_write_b32 v60, v90
	s_waitcnt vmcnt(28)
	ds_write_b32 v62, v91
	s_waitcnt vmcnt(27)
	ds_write_b32 v64, v92
	s_waitcnt vmcnt(26)
	ds_write_b32 v66, v93
	s_waitcnt vmcnt(25)
	ds_write_b32 v68, v94
	s_waitcnt vmcnt(24)
	ds_write_b32 v70, v95
	s_waitcnt vmcnt(23)
	ds_write_b32 v72, v96
	s_waitcnt vmcnt(22)
	ds_write_b32 v74, v97
	s_waitcnt vmcnt(21)
	ds_write_b32 v76, v98
	s_waitcnt vmcnt(20)
	ds_write_b32 v78, v99
	s_waitcnt vmcnt(19)
	ds_write_b32 v80, v100
	s_waitcnt vmcnt(18)
	ds_write_b32 v82, v101
	s_waitcnt vmcnt(17)
	ds_write_b32 v84, v102
	s_waitcnt vmcnt(16)
	ds_write_b32 v86, v103
	s_waitcnt vmcnt(15)
	ds_write_b32 v104, v136
	s_waitcnt vmcnt(14)
	ds_write_b32 v106, v137
	s_waitcnt vmcnt(13)
	ds_write_b32 v108, v138
	s_waitcnt vmcnt(12)
	ds_write_b32 v110, v139
	s_waitcnt vmcnt(11)
	ds_write_b32 v112, v140
	s_waitcnt vmcnt(10)
	ds_write_b32 v114, v141
	s_waitcnt vmcnt(9)
	ds_write_b32 v116, v142
	s_waitcnt vmcnt(8)
	ds_write_b32 v118, v143
	s_waitcnt vmcnt(7)
	ds_write_b32 v120, v144
	s_waitcnt vmcnt(6)
	ds_write_b32 v122, v145
	s_waitcnt vmcnt(5)
	ds_write_b32 v124, v146
	s_waitcnt vmcnt(4)
	ds_write_b32 v126, v147
	s_waitcnt vmcnt(3)
	ds_write_b32 v128, v148
	s_waitcnt vmcnt(2)
	ds_write_b32 v130, v149
	s_waitcnt vmcnt(1)
	ds_write_b32 v132, v150
	s_waitcnt vmcnt(0)
	ds_write_b32 v134, v151
	s_waitcnt lgkmcnt(0)
	s_cmp_lt_i32 s8, 32
	s_cbranch_scc1 .LBB0_391
	s_lshl_b32 s9, s8, 6
	s_and_b32 s8, s14, 0x60
	s_cmpk_gt_u32 s14, 0x7ff
	s_mov_b64 s[36:37], -1
	s_cbranch_scc0 .LBB0_389
	s_add_i32 s14, s9, 0x7ffff000
	s_and_b32 s14, s14, 0x7fffff00
	s_or_b32 s14, s14, s8
	s_addk_i32 s14, 0x480
	s_mov_b64 s[36:37], 0

.LBB0_395:
	s_lshl_b32 s8, s18, 1
	s_lshl_b32 s9, s15, 1
	v_add_u32_e32 v58, s8, v36
	v_add_u32_e32 v56, s9, v31
	v_add_u32_e32 v60, s9, v33
	v_add_u32_e32 v62, s8, v38
	v_add_u32_e32 v64, s9, v37
	v_add_u32_e32 v66, s8, v40
	v_add_u32_e32 v68, s9, v39
	v_add_u32_e32 v70, s8, v42
	v_add_u32_e32 v72, s9, v41
	v_add_u32_e32 v74, s8, v44
	v_add_u32_e32 v76, s9, v43
	v_add_u32_e32 v78, s8, v46
	v_add_u32_e32 v80, s9, v45
	v_add_u32_e32 v82, s8, v48
	v_add_u32_e32 v84, s9, v47
	v_add_u32_e32 v86, s8, v50
	v_ashrrev_i32_e32 v59, 31, v58
	v_ashrrev_i32_e32 v57, 31, v56
	v_ashrrev_i32_e32 v63, 31, v62
	v_ashrrev_i32_e32 v61, 31, v60
	v_ashrrev_i32_e32 v67, 31, v66
	v_ashrrev_i32_e32 v65, 31, v64
	v_ashrrev_i32_e32 v71, 31, v70
	v_ashrrev_i32_e32 v69, 31, v68
	v_ashrrev_i32_e32 v75, 31, v74
	v_ashrrev_i32_e32 v73, 31, v72
	v_ashrrev_i32_e32 v79, 31, v78
	v_ashrrev_i32_e32 v77, 31, v76
	v_ashrrev_i32_e32 v83, 31, v82
	v_ashrrev_i32_e32 v81, 31, v80
	v_ashrrev_i32_e32 v87, 31, v86
	v_ashrrev_i32_e32 v85, 31, v84
	v_lshlrev_b64 v[58:59], 12, v[58:59]
	v_lshlrev_b64 v[56:57], 12, v[56:57]
	v_lshlrev_b64 v[60:61], 12, v[60:61]
	v_lshlrev_b64 v[62:63], 12, v[62:63]
	v_lshlrev_b64 v[64:65], 12, v[64:65]
	v_lshlrev_b64 v[66:67], 12, v[66:67]
	v_lshlrev_b64 v[68:69], 12, v[68:69]
	v_lshlrev_b64 v[70:71], 12, v[70:71]
	v_lshlrev_b64 v[72:73], 12, v[72:73]
	v_lshlrev_b64 v[74:75], 12, v[74:75]
	v_lshlrev_b64 v[76:77], 12, v[76:77]
	v_lshlrev_b64 v[78:79], 12, v[78:79]
	v_lshlrev_b64 v[80:81], 12, v[80:81]
	v_lshlrev_b64 v[82:83], 12, v[82:83]
	v_lshlrev_b64 v[84:85], 12, v[84:85]
	v_lshlrev_b64 v[86:87], 12, v[86:87]
	v_lshl_add_u64 v[58:59], v[34:35], 0, v[58:59]
	v_lshl_add_u64 v[56:57], v[34:35], 0, v[56:57]
	v_lshl_add_u64 v[62:63], v[34:35], 0, v[62:63]
	v_lshl_add_u64 v[60:61], v[34:35], 0, v[60:61]
	v_lshl_add_u64 v[66:67], v[34:35], 0, v[66:67]
	v_lshl_add_u64 v[64:65], v[34:35], 0, v[64:65]
	v_lshl_add_u64 v[70:71], v[34:35], 0, v[70:71]
	v_lshl_add_u64 v[68:69], v[34:35], 0, v[68:69]
	v_lshl_add_u64 v[74:75], v[34:35], 0, v[74:75]
	v_lshl_add_u64 v[72:73], v[34:35], 0, v[72:73]
	v_lshl_add_u64 v[78:79], v[34:35], 0, v[78:79]
	v_lshl_add_u64 v[76:77], v[34:35], 0, v[76:77]
	v_lshl_add_u64 v[82:83], v[34:35], 0, v[82:83]
	v_lshl_add_u64 v[80:81], v[34:35], 0, v[80:81]
	v_lshl_add_u64 v[86:87], v[34:35], 0, v[86:87]
	v_lshl_add_u64 v[84:85], v[34:35], 0, v[84:85]
	global_load_dword v88, v[58:59], off
	global_load_dword v89, v[56:57], off
	global_load_dword v90, v[62:63], off
	global_load_dword v91, v[60:61], off
	global_load_dword v92, v[66:67], off
	global_load_dword v93, v[64:65], off
	global_load_dword v94, v[70:71], off
	global_load_dword v95, v[68:69], off
	global_load_dword v96, v[74:75], off
	global_load_dword v97, v[72:73], off
	global_load_dword v98, v[78:79], off
	global_load_dword v99, v[76:77], off
	global_load_dword v100, v[82:83], off
	global_load_dword v101, v[80:81], off
	global_load_dword v102, v[86:87], off
	global_load_dword v103, v[84:85], off
	s_add_i32 s18, s18, 16
	s_add_i32 s15, s15, 16
	s_add_i32 s19, s19, -16
	v_add_u32_e32 v56, s8, v0
	v_add_u32_e32 v58, s9, v1
	v_add_u32_e32 v62, s9, v5
	v_add_u32_e32 v60, s8, v20
	v_add_u32_e32 v66, s9, v7
	v_add_u32_e32 v64, s8, v22
	v_add_u32_e32 v70, s9, v21
	v_add_u32_e32 v68, s8, v24
	v_add_u32_e32 v74, s9, v23
	v_add_u32_e32 v72, s8, v26
	v_add_u32_e32 v78, s9, v25
	v_add_u32_e32 v76, s8, v28
	v_add_u32_e32 v82, s9, v27
	v_add_u32_e32 v80, s8, v30
	v_add_u32_e32 v86, s9, v29
	v_add_u32_e32 v84, s8, v32
	s_cmp_lg_u32 s19, 0
	v_mad_u64_u32 v[56:57], s[8:9], v56, s16, v[4:5]
	v_mad_u64_u32 v[58:59], s[8:9], v58, s16, v[4:5]
	v_mad_u64_u32 v[60:61], s[8:9], v60, s16, v[4:5]
	v_mad_u64_u32 v[62:63], s[8:9], v62, s16, v[4:5]
	v_mad_u64_u32 v[64:65], s[8:9], v64, s16, v[4:5]
	v_mad_u64_u32 v[66:67], s[8:9], v66, s16, v[4:5]
	v_mad_u64_u32 v[68:69], s[8:9], v68, s16, v[4:5]
	v_mad_u64_u32 v[70:71], s[8:9], v70, s16, v[4:5]
	v_mad_u64_u32 v[72:73], s[8:9], v72, s16, v[4:5]
	v_mad_u64_u32 v[74:75], s[8:9], v74, s16, v[4:5]
	v_mad_u64_u32 v[76:77], s[8:9], v76, s16, v[4:5]
	v_mad_u64_u32 v[78:79], s[8:9], v78, s16, v[4:5]
	v_mad_u64_u32 v[80:81], s[8:9], v80, s16, v[4:5]
	v_mad_u64_u32 v[82:83], s[8:9], v82, s16, v[4:5]
	v_mad_u64_u32 v[84:85], s[8:9], v84, s16, v[4:5]
	v_mad_u64_u32 v[86:87], s[8:9], v86, s16, v[4:5]
	s_lshl_b32 s8, s18, 1
	s_lshl_b32 s9, s15, 1
	v_add_u32_e32 v106, s8, v36
	v_add_u32_e32 v104, s9, v31
	v_add_u32_e32 v108, s9, v33
	v_add_u32_e32 v110, s8, v38
	v_add_u32_e32 v112, s9, v37
	v_add_u32_e32 v114, s8, v40
	v_add_u32_e32 v116, s9, v39
	v_add_u32_e32 v118, s8, v42
	v_add_u32_e32 v120, s9, v41
	v_add_u32_e32 v122, s8, v44
	v_add_u32_e32 v124, s9, v43
	v_add_u32_e32 v126, s8, v46
	v_add_u32_e32 v128, s9, v45
	v_add_u32_e32 v130, s8, v48
	v_add_u32_e32 v132, s9, v47
	v_add_u32_e32 v134, s8, v50
	v_ashrrev_i32_e32 v107, 31, v106
	v_ashrrev_i32_e32 v105, 31, v104
	v_ashrrev_i32_e32 v111, 31, v110
	v_ashrrev_i32_e32 v109, 31, v108
	v_ashrrev_i32_e32 v115, 31, v114
	v_ashrrev_i32_e32 v113, 31, v112
	v_ashrrev_i32_e32 v119, 31, v118
	v_ashrrev_i32_e32 v117, 31, v116
	v_ashrrev_i32_e32 v123, 31, v122
	v_ashrrev_i32_e32 v121, 31, v120
	v_ashrrev_i32_e32 v127, 31, v126
	v_ashrrev_i32_e32 v125, 31, v124
	v_ashrrev_i32_e32 v131, 31, v130
	v_ashrrev_i32_e32 v129, 31, v128
	v_ashrrev_i32_e32 v135, 31, v134
	v_ashrrev_i32_e32 v133, 31, v132
	v_lshlrev_b64 v[106:107], 12, v[106:107]
	v_lshlrev_b64 v[104:105], 12, v[104:105]
	v_lshlrev_b64 v[108:109], 12, v[108:109]
	v_lshlrev_b64 v[110:111], 12, v[110:111]
	v_lshlrev_b64 v[112:113], 12, v[112:113]
	v_lshlrev_b64 v[114:115], 12, v[114:115]
	v_lshlrev_b64 v[116:117], 12, v[116:117]
	v_lshlrev_b64 v[118:119], 12, v[118:119]
	v_lshlrev_b64 v[120:121], 12, v[120:121]
	v_lshlrev_b64 v[122:123], 12, v[122:123]
	v_lshlrev_b64 v[124:125], 12, v[124:125]
	v_lshlrev_b64 v[126:127], 12, v[126:127]
	v_lshlrev_b64 v[128:129], 12, v[128:129]
	v_lshlrev_b64 v[130:131], 12, v[130:131]
	v_lshlrev_b64 v[132:133], 12, v[132:133]
	v_lshlrev_b64 v[134:135], 12, v[134:135]
	v_lshl_add_u64 v[106:107], v[34:35], 0, v[106:107]
	v_lshl_add_u64 v[104:105], v[34:35], 0, v[104:105]
	v_lshl_add_u64 v[110:111], v[34:35], 0, v[110:111]
	v_lshl_add_u64 v[108:109], v[34:35], 0, v[108:109]
	v_lshl_add_u64 v[114:115], v[34:35], 0, v[114:115]
	v_lshl_add_u64 v[112:113], v[34:35], 0, v[112:113]
	v_lshl_add_u64 v[118:119], v[34:35], 0, v[118:119]
	v_lshl_add_u64 v[116:117], v[34:35], 0, v[116:117]
	v_lshl_add_u64 v[122:123], v[34:35], 0, v[122:123]
	v_lshl_add_u64 v[120:121], v[34:35], 0, v[120:121]
	v_lshl_add_u64 v[126:127], v[34:35], 0, v[126:127]
	v_lshl_add_u64 v[124:125], v[34:35], 0, v[124:125]
	v_lshl_add_u64 v[130:131], v[34:35], 0, v[130:131]
	v_lshl_add_u64 v[128:129], v[34:35], 0, v[128:129]
	v_lshl_add_u64 v[134:135], v[34:35], 0, v[134:135]
	v_lshl_add_u64 v[132:133], v[34:35], 0, v[132:133]
	global_load_dword v136, v[106:107], off
	global_load_dword v137, v[104:105], off
	global_load_dword v138, v[110:111], off
	global_load_dword v139, v[108:109], off
	global_load_dword v140, v[114:115], off
	global_load_dword v141, v[112:113], off
	global_load_dword v142, v[118:119], off
	global_load_dword v143, v[116:117], off
	global_load_dword v144, v[122:123], off
	global_load_dword v145, v[120:121], off
	global_load_dword v146, v[126:127], off
	global_load_dword v147, v[124:125], off
	global_load_dword v148, v[130:131], off
	global_load_dword v149, v[128:129], off
	global_load_dword v150, v[134:135], off
	global_load_dword v151, v[132:133], off
	s_add_i32 s18, s18, 16
	s_add_i32 s15, s15, 16
	s_add_i32 s19, s19, -16
	v_add_u32_e32 v104, s8, v0
	v_add_u32_e32 v106, s9, v1
	v_add_u32_e32 v110, s9, v5
	v_add_u32_e32 v108, s8, v20
	v_add_u32_e32 v114, s9, v7
	v_add_u32_e32 v112, s8, v22
	v_add_u32_e32 v118, s9, v21
	v_add_u32_e32 v116, s8, v24
	v_add_u32_e32 v122, s9, v23
	v_add_u32_e32 v120, s8, v26
	v_add_u32_e32 v126, s9, v25
	v_add_u32_e32 v124, s8, v28
	v_add_u32_e32 v130, s9, v27
	v_add_u32_e32 v128, s8, v30
	v_add_u32_e32 v134, s9, v29
	v_add_u32_e32 v132, s8, v32
	s_cmp_lg_u32 s19, 0
	v_mad_u64_u32 v[104:105], s[8:9], v104, s16, v[4:5]
	v_mad_u64_u32 v[106:107], s[8:9], v106, s16, v[4:5]
	v_mad_u64_u32 v[108:109], s[8:9], v108, s16, v[4:5]
	v_mad_u64_u32 v[110:111], s[8:9], v110, s16, v[4:5]
	v_mad_u64_u32 v[112:113], s[8:9], v112, s16, v[4:5]
	v_mad_u64_u32 v[114:115], s[8:9], v114, s16, v[4:5]
	v_mad_u64_u32 v[116:117], s[8:9], v116, s16, v[4:5]
	v_mad_u64_u32 v[118:119], s[8:9], v118, s16, v[4:5]
	v_mad_u64_u32 v[120:121], s[8:9], v120, s16, v[4:5]
	v_mad_u64_u32 v[122:123], s[8:9], v122, s16, v[4:5]
	v_mad_u64_u32 v[124:125], s[8:9], v124, s16, v[4:5]
	v_mad_u64_u32 v[126:127], s[8:9], v126, s16, v[4:5]
	v_mad_u64_u32 v[128:129], s[8:9], v128, s16, v[4:5]
	v_mad_u64_u32 v[130:131], s[8:9], v130, s16, v[4:5]
	v_mad_u64_u32 v[132:133], s[8:9], v132, s16, v[4:5]
	v_mad_u64_u32 v[134:135], s[8:9], v134, s16, v[4:5]
	s_waitcnt vmcnt(31)
	ds_write_b32 v56, v88
	s_waitcnt vmcnt(30)
	ds_write_b32 v58, v89
	s_waitcnt vmcnt(29)
	ds_write_b32 v60, v90
	s_waitcnt vmcnt(28)
	ds_write_b32 v62, v91
	s_waitcnt vmcnt(27)
	ds_write_b32 v64, v92
	s_waitcnt vmcnt(26)
	ds_write_b32 v66, v93
	s_waitcnt vmcnt(25)
	ds_write_b32 v68, v94
	s_waitcnt vmcnt(24)
	ds_write_b32 v70, v95
	s_waitcnt vmcnt(23)
	ds_write_b32 v72, v96
	s_waitcnt vmcnt(22)
	ds_write_b32 v74, v97
	s_waitcnt vmcnt(21)
	ds_write_b32 v76, v98
	s_waitcnt vmcnt(20)
	ds_write_b32 v78, v99
	s_waitcnt vmcnt(19)
	ds_write_b32 v80, v100
	s_waitcnt vmcnt(18)
	ds_write_b32 v82, v101
	s_waitcnt vmcnt(17)
	ds_write_b32 v84, v102
	s_waitcnt vmcnt(16)
	ds_write_b32 v86, v103
	s_waitcnt vmcnt(15)
	ds_write_b32 v104, v136
	s_waitcnt vmcnt(14)
	ds_write_b32 v106, v137
	s_waitcnt vmcnt(13)
	ds_write_b32 v108, v138
	s_waitcnt vmcnt(12)
	ds_write_b32 v110, v139
	s_waitcnt vmcnt(11)
	ds_write_b32 v112, v140
	s_waitcnt vmcnt(10)
	ds_write_b32 v114, v141
	s_waitcnt vmcnt(9)
	ds_write_b32 v116, v142
	s_waitcnt vmcnt(8)
	ds_write_b32 v118, v143
	s_waitcnt vmcnt(7)
	ds_write_b32 v120, v144
	s_waitcnt vmcnt(6)
	ds_write_b32 v122, v145
	s_waitcnt vmcnt(5)
	ds_write_b32 v124, v146
	s_waitcnt vmcnt(4)
	ds_write_b32 v126, v147
	s_waitcnt vmcnt(3)
	ds_write_b32 v128, v148
	s_waitcnt vmcnt(2)
	ds_write_b32 v130, v149
	s_waitcnt vmcnt(1)
	ds_write_b32 v132, v150
	s_waitcnt vmcnt(0)
	ds_write_b32 v134, v151
	s_waitcnt lgkmcnt(0)
	v_add_u32_e32 v40, s14, v49
	ds_read2_b32 v[34:35], v51 offset1:33
	s_lshl_b32 s0, s0, 1
	v_ashrrev_i32_e32 v41, 31, v40
	s_waitcnt lgkmcnt(0)
	v_cvt_pk_bf16_f32 v34, v34, v35
	ds_read2_b32 v[36:37], v51 offset0:66 offset1:99
	v_lshl_add_u64 v[42:43], v[18:19], 0, s[0:1]
	v_lshlrev_b64 v[40:41], 11, v[40:41]
	s_waitcnt lgkmcnt(0)
	v_cvt_pk_bf16_f32 v35, v36, v37
	ds_read2_b32 v[36:37], v51 offset0:132 offset1:165
	v_lshl_add_u64 v[40:41], v[42:43], 0, v[40:41]
	s_waitcnt lgkmcnt(0)
	v_cvt_pk_bf16_f32 v36, v36, v37
	ds_read2_b32 v[38:39], v51 offset0:198 offset1:231
	s_waitcnt lgkmcnt(0)
	v_cvt_pk_bf16_f32 v37, v38, v39
	global_store_dwordx4 v[40:41], v[34:37], off
	v_add_u32_e32 v40, s14, v52
	v_ashrrev_i32_e32 v41, 31, v40
	ds_read2_b32 v[38:39], v51 offset0:8 offset1:41
	s_waitcnt lgkmcnt(0)
	v_cvt_pk_bf16_f32 v34, v38, v39
	ds_read2_b32 v[36:37], v51 offset0:74 offset1:107
	v_lshlrev_b64 v[40:41], 11, v[40:41]
	s_waitcnt lgkmcnt(0)
	v_cvt_pk_bf16_f32 v35, v36, v37
	ds_read2_b32 v[36:37], v51 offset0:140 offset1:173
	v_lshl_add_u64 v[40:41], v[42:43], 0, v[40:41]
	s_waitcnt lgkmcnt(0)
	v_cvt_pk_bf16_f32 v36, v36, v37
	ds_read2_b32 v[38:39], v51 offset0:206 offset1:239
	s_waitcnt lgkmcnt(0)
	v_cvt_pk_bf16_f32 v37, v38, v39
	global_store_dwordx4 v[40:41], v[34:37], off
	v_add_u32_e32 v40, s14, v53
	ds_read2_b32 v[38:39], v51 offset0:16 offset1:49
	s_waitcnt lgkmcnt(0)
	v_cvt_pk_bf16_f32 v34, v38, v39
	ds_read2_b32 v[36:37], v51 offset0:82 offset1:115
	v_ashrrev_i32_e32 v41, 31, v40
	s_waitcnt lgkmcnt(0)
	v_cvt_pk_bf16_f32 v35, v36, v37
	ds_read2_b32 v[36:37], v51 offset0:148 offset1:181
	v_lshlrev_b64 v[40:41], 11, v[40:41]
	s_waitcnt lgkmcnt(0)
	v_cvt_pk_bf16_f32 v36, v36, v37
	ds_read2_b32 v[38:39], v51 offset0:214 offset1:247
	s_waitcnt lgkmcnt(0)
	v_cvt_pk_bf16_f32 v37, v38, v39
	v_lshl_add_u64 v[40:41], v[42:43], 0, v[40:41]
	ds_read2_b32 v[38:39], v51 offset0:24 offset1:57
	global_store_dwordx4 v[40:41], v[34:37], off
	v_add_u32_e32 v40, s14, v54
	v_ashrrev_i32_e32 v41, 31, v40
	s_waitcnt lgkmcnt(0)
	v_cvt_pk_bf16_f32 v34, v38, v39
	ds_read2_b32 v[36:37], v51 offset0:90 offset1:123
	s_waitcnt lgkmcnt(0)
	v_cvt_pk_bf16_f32 v35, v36, v37
	ds_read2_b32 v[36:37], v51 offset0:156 offset1:189
	s_waitcnt lgkmcnt(0)
	v_cvt_pk_bf16_f32 v36, v36, v37
	ds_read2_b32 v[38:39], v51 offset0:222 offset1:255
	v_lshlrev_b64 v[40:41], 11, v[40:41]
	s_waitcnt lgkmcnt(0)
	v_cvt_pk_bf16_f32 v37, v38, v39
	v_lshl_add_u64 v[38:39], v[42:43], 0, v[40:41]
	global_store_dwordx4 v[38:39], v[34:37], off
	s_waitcnt lgkmcnt(0)
	s_branch .LBB0_358
